# P8 GEMM K-loop: LDS-DMA with SGPR base + 32-bit VGPR offset addressing (64-bit VALU address adds removed); on top of v138
# speedup vs baseline: 1.0237x; 1.0035x over previous
; #define PG8_STAGE(bufoff, gbase, voff) do { _Pragma("unroll") for (int _i = 0; _i < 2; ++_i) \
;     __builtin_amdgcn_global_load_lds((const unsigned*)((const char*)(gbase) + (voff)[_i]), (LAS unsigned*)(lds + (bufoff) + ldsw + _i * 8192), 16, 0, 0); } while (0)
; #define PG8_LDA(dst, b, h) do { _Pragma("unroll") for (int m = 0; m < 4; ++m) _Pragma("unroll") for (int k = 0; k < 2; ++k) dst[m][k] = *(const LAS bf16x8*)(lds + PG8_SA(b, h) + aoff + m * 2048 + k * 1024); } while (0)
; #define PG8_LDB(dst, b, h) do { _Pragma("unroll") for (int n = 0; n < 2; ++n) _Pragma("unroll") for (int k = 0; k < 2; ++k) dst[n][k] = *(const LAS bf16x8*)(lds + PG8_SB(b, h) + boff + n * 2048 + k * 1024); } while (0)
; #define PG8_WAIT_V(n) asm volatile("s_waitcnt vmcnt(" #n ")" ::: "memory")
; template <class Epi>
; __device__ __forceinline__ void gemm_phase(LAS unsigned char* lds, const Gemm g, const StaticOrder& S, const Epi& E) {
;     ...
;     for (int t = 0; t < nt; t += 2) {
;       const bool last = (t == nt - 2);
;       const char* a1 = cA + (size_t)(t + 1) * kstep;
;       const char* a2 = last ? nA : cA + (size_t)(t + 2) * kstep; const char* b2 = last ? nB : cB + (size_t)(t + 2) * kstep;
;       const char* a3 = a2 + kstep; const char* b3 = b2 + kstep;
;       PG8_LDB(B0, 0, 0); PG8_SCHED; PG8_LDA(At, 0, 0); PG8_STAGE(PG8_SA(1, 1), a1 + hstep, voffA);
;       PG8_WAIT_L(8); PG8_BAR; PG8_WAIT_L(0); PG8_MMA(0, 0, At, B0); PG8_BAR; PG8_SCHED;
;       PG8_LDB(B1, 0, 1); PG8_STAGE(PG8_SB(0, 0), b2, voffB);
;       PG8_BAR; PG8_WAIT_L(0); PG8_MMA(0, 1, At, B1); PG8_BAR;
;       PG8_LDA(At, 0, 1); PG8_STAGE(PG8_SA(0, 0), a2, voffA);
;       PG8_BAR; PG8_WAIT_L(0); PG8_MMA(1, 0, At, B0); PG8_BAR; PG8_SCHED;
;       PG8_STAGE(PG8_SB(0, 1), b2 + hstep, voffB);
;       PG8_WAIT_V(6); PG8_BAR; PG8_MMA(1, 1, At, B1); PG8_BAR;
;       PG8_LDB(B0, 1, 0); PG8_SCHED; PG8_LDA(At, 1, 0); PG8_STAGE(PG8_SA(0, 1), a2 + hstep, voffA);
;       PG8_WAIT_L(8); PG8_BAR; PG8_WAIT_L(0); PG8_MMA(0, 0, At, B0); PG8_BAR; PG8_SCHED;
;       PG8_LDB(B1, 1, 1); PG8_STAGE(PG8_SB(1, 0), b3, voffB);
;       PG8_BAR; PG8_WAIT_L(0); PG8_MMA(0, 1, At, B1); PG8_BAR;
;       PG8_LDA(At, 1, 1); PG8_STAGE(PG8_SA(1, 0), a3, voffA);
;       PG8_BAR; PG8_WAIT_L(0); PG8_MMA(1, 0, At, B0); PG8_BAR; PG8_SCHED;
;       PG8_STAGE(PG8_SB(1, 1), b3 + hstep, voffB);
;       PG8_WAIT_V(6); PG8_BAR; PG8_MMA(1, 1, At, B1); PG8_BAR;
.LBB0_874:
	ds_read_b128 v[154:157], v150
	ds_read_b128 v[158:161], v150 offset:1024
	ds_read_b128 v[162:165], v150 offset:2048
	ds_read_b128 v[166:169], v150 offset:3072
	s_add_i32 s59, s24, 2
	s_add_u32 s26, s0, 0x80
	s_addc_u32 s25, s1, 0
	s_cmp_eq_u32 s48, s24
	s_cselect_b32 s24, s4, s26
	s_cselect_b32 s25, s5, s25
	s_cselect_b32 s27, s23, s58
	s_cselect_b32 s26, s22, s57
	s_add_i32 m0, s38, 0xc000
	ds_read_b128 v[170:173], v151
	ds_read_b128 v[174:177], v151 offset:1024
	ds_read_b128 v[178:181], v151 offset:2048
	ds_read_b128 v[182:185], v151 offset:3072
	ds_read_b128 v[188:191], v151 offset:4096
	ds_read_b128 v[194:197], v151 offset:5120
	ds_read_b128 v[198:201], v151 offset:6144
	ds_read_b128 v[202:205], v151 offset:7168
	global_load_lds_dwordx4 v138, s[0:1]
	s_add_i32 m0, s38, 0xe000
	s_nop 0
	global_load_lds_dwordx4 v140, s[0:1]
	s_waitcnt lgkmcnt(8)
	s_barrier
	s_waitcnt lgkmcnt(0)
	s_setprio 1
	s_waitcnt lgkmcnt(0)
	v_mfma_f32_16x16x32_bf16 v[108:111], v[154:157], v[170:173], v[108:111]
	v_mfma_f32_16x16x32_bf16 v[112:115], v[162:165], v[170:173], v[112:115]
	v_mfma_f32_16x16x32_bf16 v[104:107], v[154:157], v[178:181], v[104:107]
	v_mfma_f32_16x16x32_bf16 v[96:99], v[162:165], v[178:181], v[96:99]
	v_mfma_f32_16x16x32_bf16 v[88:91], v[154:157], v[188:191], v[88:91]
	v_mfma_f32_16x16x32_bf16 v[80:83], v[162:165], v[188:191], v[80:83]
	v_mfma_f32_16x16x32_bf16 v[72:75], v[154:157], v[198:201], v[72:75]
	v_mfma_f32_16x16x32_bf16 v[64:67], v[162:165], v[198:201], v[64:67]
	v_mfma_f32_16x16x32_bf16 v[108:111], v[158:161], v[174:177], v[108:111]
	v_mfma_f32_16x16x32_bf16 v[112:115], v[166:169], v[174:177], v[112:115]
	v_mfma_f32_16x16x32_bf16 v[104:107], v[158:161], v[182:185], v[104:107]
	v_mfma_f32_16x16x32_bf16 v[96:99], v[166:169], v[182:185], v[96:99]
	v_mfma_f32_16x16x32_bf16 v[88:91], v[158:161], v[194:197], v[88:91]
	v_mfma_f32_16x16x32_bf16 v[80:83], v[166:169], v[194:197], v[80:83]
	v_mfma_f32_16x16x32_bf16 v[72:75], v[158:161], v[202:205], v[72:75]
	v_mfma_f32_16x16x32_bf16 v[64:67], v[166:169], v[202:205], v[64:67]
	s_setprio 0
	s_barrier
	s_add_i32 s60, s49, s33
	s_mov_b64 s[92:93], s[26:27]
	s_mov_b32 m0, s60
	ds_read_b128 v[206:209], v152
	ds_read_b128 v[210:213], v152 offset:1024
	ds_read_b128 v[214:217], v152 offset:2048
	ds_read_b128 v[218:221], v152 offset:3072
	global_load_lds_dwordx4 v132, s[26:27]
	s_add_i32 m0, s60, 0x2000
	s_nop 0
	global_load_lds_dwordx4 v128, s[26:27]
	s_barrier
	s_waitcnt lgkmcnt(0)
	s_setprio 1
	s_waitcnt lgkmcnt(0)
	v_mfma_f32_16x16x32_bf16 v[124:127], v[206:209], v[170:173], v[124:127]
	v_mfma_f32_16x16x32_bf16 v[120:123], v[214:217], v[170:173], v[120:123]
	v_mfma_f32_16x16x32_bf16 v[116:119], v[206:209], v[178:181], v[116:119]
	v_mfma_f32_16x16x32_bf16 v[100:103], v[214:217], v[178:181], v[100:103]
	v_mfma_f32_16x16x32_bf16 v[92:95], v[206:209], v[188:191], v[92:95]
	v_mfma_f32_16x16x32_bf16 v[84:87], v[214:217], v[188:191], v[84:87]
	v_mfma_f32_16x16x32_bf16 v[76:79], v[206:209], v[198:201], v[76:79]
	v_mfma_f32_16x16x32_bf16 v[68:71], v[214:217], v[198:201], v[68:71]
	v_mfma_f32_16x16x32_bf16 v[124:127], v[210:213], v[174:177], v[124:127]
	v_mfma_f32_16x16x32_bf16 v[120:123], v[218:221], v[174:177], v[120:123]
	v_mfma_f32_16x16x32_bf16 v[116:119], v[210:213], v[182:185], v[116:119]
	v_mfma_f32_16x16x32_bf16 v[100:103], v[218:221], v[182:185], v[100:103]
	v_mfma_f32_16x16x32_bf16 v[92:95], v[210:213], v[194:197], v[92:95]
	v_mfma_f32_16x16x32_bf16 v[84:87], v[218:221], v[194:197], v[84:87]
	v_mfma_f32_16x16x32_bf16 v[76:79], v[210:213], v[202:205], v[76:79]
	v_mfma_f32_16x16x32_bf16 v[68:71], v[218:221], v[202:205], v[68:71]
	s_setprio 0
	s_mov_b32 m0, s38
	s_mov_b64 s[96:97], s[24:25]
	s_barrier
	ds_read_b128 v[170:173], v151 offset:16384
	ds_read_b128 v[174:177], v151 offset:17408
	ds_read_b128 v[178:181], v151 offset:18432
	ds_read_b128 v[182:185], v151 offset:19456
	ds_read_b128 v[188:191], v151 offset:20480
	ds_read_b128 v[194:197], v151 offset:21504
	ds_read_b128 v[198:201], v151 offset:22528
	ds_read_b128 v[202:205], v151 offset:23552
	global_load_lds_dwordx4 v134, s[24:25]
	s_mov_b32 m0, s39
	s_nop 0
	global_load_lds_dwordx4 v130, s[24:25]
	s_barrier
	s_waitcnt lgkmcnt(0)
	s_setprio 1
	s_waitcnt lgkmcnt(0)
	v_mfma_f32_16x16x32_bf16 v[56:59], v[154:157], v[170:173], v[56:59]
	v_mfma_f32_16x16x32_bf16 v[52:55], v[162:165], v[170:173], v[52:55]
	v_mfma_f32_16x16x32_bf16 v[40:43], v[154:157], v[178:181], v[40:43]
	v_mfma_f32_16x16x32_bf16 v[36:39], v[162:165], v[178:181], v[36:39]
	v_mfma_f32_16x16x32_bf16 v[24:27], v[154:157], v[188:191], v[24:27]
	v_mfma_f32_16x16x32_bf16 v[20:23], v[162:165], v[188:191], v[20:23]
	v_mfma_f32_16x16x32_bf16 v[8:11], v[154:157], v[198:201], v[8:11]
	v_mfma_f32_16x16x32_bf16 v[4:7], v[162:165], v[198:201], v[4:7]
	v_mfma_f32_16x16x32_bf16 v[56:59], v[158:161], v[174:177], v[56:59]
	v_mfma_f32_16x16x32_bf16 v[52:55], v[166:169], v[174:177], v[52:55]
	v_mfma_f32_16x16x32_bf16 v[40:43], v[158:161], v[182:185], v[40:43]
	v_mfma_f32_16x16x32_bf16 v[36:39], v[166:169], v[182:185], v[36:39]
	v_mfma_f32_16x16x32_bf16 v[24:27], v[158:161], v[194:197], v[24:27]
	v_mfma_f32_16x16x32_bf16 v[20:23], v[166:169], v[194:197], v[20:23]
	v_mfma_f32_16x16x32_bf16 v[8:11], v[158:161], v[202:205], v[8:11]
	v_mfma_f32_16x16x32_bf16 v[4:7], v[166:169], v[202:205], v[4:7]
	s_setprio 0
	s_barrier
	s_add_u32 s26, s26, s6
	s_addc_u32 s27, s27, s7
	s_add_i32 s60, s50, s33
	s_mov_b64 s[100:101], s[26:27]
	s_mov_b32 m0, s60
	global_load_lds_dwordx4 v132, s[26:27]
	s_add_i32 m0, s60, 0x2000
	s_nop 0
	global_load_lds_dwordx4 v128, s[26:27]
	s_waitcnt vmcnt(6)
	s_barrier
; #define PG8_STAGE(bufoff, gbase, voff) do { _Pragma("unroll") for (int _i = 0; _i < 2; ++_i) \
;     __builtin_amdgcn_global_load_lds((const unsigned*)((const char*)(gbase) + (voff)[_i]), (LAS unsigned*)(lds + (bufoff) + ldsw + _i * 8192), 16, 0, 0); } while (0)
; #define PG8_LDA(dst, b, h) do { _Pragma("unroll") for (int m = 0; m < 4; ++m) _Pragma("unroll") for (int k = 0; k < 2; ++k) dst[m][k] = *(const LAS bf16x8*)(lds + PG8_SA(b, h) + aoff + m * 2048 + k * 1024); } while (0)
; #define PG8_LDB(dst, b, h) do { _Pragma("unroll") for (int n = 0; n < 2; ++n) _Pragma("unroll") for (int k = 0; k < 2; ++k) dst[n][k] = *(const LAS bf16x8*)(lds + PG8_SB(b, h) + boff + n * 2048 + k * 1024); } while (0)
; #define PG8_WAIT_V(n) asm volatile("s_waitcnt vmcnt(" #n ")" ::: "memory")
; template <class Epi>
; __device__ __forceinline__ void gemm_phase(LAS unsigned char* lds, const Gemm g, const StaticOrder& S, const Epi& E) {
;     ...
;     for (int t = 0; t < nt; t += 2) {
;       const bool last = (t == nt - 2);
;       const char* a1 = cA + (size_t)(t + 1) * kstep;
;       const char* a2 = last ? nA : cA + (size_t)(t + 2) * kstep; const char* b2 = last ? nB : cB + (size_t)(t + 2) * kstep;
;       const char* a3 = a2 + kstep; const char* b3 = b2 + kstep;
;       PG8_LDB(B0, 0, 0); PG8_SCHED; PG8_LDA(At, 0, 0); PG8_STAGE(PG8_SA(1, 1), a1 + hstep, voffA);
;       PG8_WAIT_L(8); PG8_BAR; PG8_WAIT_L(0); PG8_MMA(0, 0, At, B0); PG8_BAR; PG8_SCHED;
;       PG8_LDB(B1, 0, 1); PG8_STAGE(PG8_SB(0, 0), b2, voffB);
;       PG8_BAR; PG8_WAIT_L(0); PG8_MMA(0, 1, At, B1); PG8_BAR;
;       PG8_LDA(At, 0, 1); PG8_STAGE(PG8_SA(0, 0), a2, voffA);
;       PG8_BAR; PG8_WAIT_L(0); PG8_MMA(1, 0, At, B0); PG8_BAR; PG8_SCHED;
;       PG8_STAGE(PG8_SB(0, 1), b2 + hstep, voffB);
;       PG8_WAIT_V(6); PG8_BAR; PG8_MMA(1, 1, At, B1); PG8_BAR;
;       PG8_LDB(B0, 1, 0); PG8_SCHED; PG8_LDA(At, 1, 0); PG8_STAGE(PG8_SA(0, 1), a2 + hstep, voffA);
;       PG8_WAIT_L(8); PG8_BAR; PG8_WAIT_L(0); PG8_MMA(0, 0, At, B0); PG8_BAR; PG8_SCHED;
;       PG8_LDB(B1, 1, 1); PG8_STAGE(PG8_SB(1, 0), b3, voffB);
;       PG8_BAR; PG8_WAIT_L(0); PG8_MMA(0, 1, At, B1); PG8_BAR;
;       PG8_LDA(At, 1, 1); PG8_STAGE(PG8_SA(1, 0), a3, voffA);
;       PG8_BAR; PG8_WAIT_L(0); PG8_MMA(1, 0, At, B0); PG8_BAR; PG8_SCHED;
;       PG8_STAGE(PG8_SB(1, 1), b3 + hstep, voffB);
;       PG8_WAIT_V(6); PG8_BAR; PG8_MMA(1, 1, At, B1); PG8_BAR;
	s_setprio 1
	v_mfma_f32_16x16x32_bf16 v[60:63], v[206:209], v[170:173], v[60:63]
	v_mfma_f32_16x16x32_bf16 v[48:51], v[214:217], v[170:173], v[48:51]
	v_mfma_f32_16x16x32_bf16 v[44:47], v[206:209], v[178:181], v[44:47]
	v_mfma_f32_16x16x32_bf16 v[32:35], v[214:217], v[178:181], v[32:35]
	v_mfma_f32_16x16x32_bf16 v[28:31], v[206:209], v[188:191], v[28:31]
	v_mfma_f32_16x16x32_bf16 v[16:19], v[214:217], v[188:191], v[16:19]
	v_mfma_f32_16x16x32_bf16 v[12:15], v[206:209], v[198:201], v[12:15]
	v_mfma_f32_16x16x32_bf16 v[0:3], v[214:217], v[198:201], v[0:3]
	v_mfma_f32_16x16x32_bf16 v[60:63], v[210:213], v[174:177], v[60:63]
	v_mfma_f32_16x16x32_bf16 v[48:51], v[218:221], v[174:177], v[48:51]
	v_mfma_f32_16x16x32_bf16 v[44:47], v[210:213], v[182:185], v[44:47]
	v_mfma_f32_16x16x32_bf16 v[32:35], v[218:221], v[182:185], v[32:35]
	v_mfma_f32_16x16x32_bf16 v[28:31], v[210:213], v[194:197], v[28:31]
	v_mfma_f32_16x16x32_bf16 v[16:19], v[218:221], v[194:197], v[16:19]
	v_mfma_f32_16x16x32_bf16 v[12:15], v[210:213], v[202:205], v[12:15]
	v_mfma_f32_16x16x32_bf16 v[0:3], v[218:221], v[202:205], v[0:3]
	s_setprio 0
	s_add_i32 s26, 0, 0x18000
	v_add_u32_e32 v166, s26, v149
	s_barrier
	ds_read_b128 v[154:157], v166
	ds_read_b128 v[158:161], v166 offset:1024
	ds_read_b128 v[162:165], v166 offset:2048
	ds_read_b128 v[166:169], v166 offset:3072
	s_add_u32 s24, s24, s6
	s_addc_u32 s25, s25, s7
	s_mov_b32 m0, s40
	ds_read_b128 v[170:173], v151 offset:32768
	ds_read_b128 v[174:177], v151 offset:33792
	ds_read_b128 v[178:181], v151 offset:34816
	ds_read_b128 v[182:185], v151 offset:35840
	ds_read_b128 v[188:191], v151 offset:36864
	ds_read_b128 v[194:197], v151 offset:37888
	ds_read_b128 v[198:201], v151 offset:38912
	ds_read_b128 v[202:205], v151 offset:39936
	global_load_lds_dwordx4 v134, s[24:25]
	s_mov_b32 m0, s41
	s_nop 0
	global_load_lds_dwordx4 v130, s[24:25]
	s_waitcnt lgkmcnt(8)
	s_barrier
	s_waitcnt lgkmcnt(0)
	s_setprio 1
	s_waitcnt lgkmcnt(0)
	v_mfma_f32_16x16x32_bf16 v[108:111], v[154:157], v[170:173], v[108:111]
	v_mfma_f32_16x16x32_bf16 v[112:115], v[162:165], v[170:173], v[112:115]
	v_mfma_f32_16x16x32_bf16 v[104:107], v[154:157], v[178:181], v[104:107]
	v_mfma_f32_16x16x32_bf16 v[96:99], v[162:165], v[178:181], v[96:99]
	v_mfma_f32_16x16x32_bf16 v[88:91], v[154:157], v[188:191], v[88:91]
	v_mfma_f32_16x16x32_bf16 v[80:83], v[162:165], v[188:191], v[80:83]
	v_mfma_f32_16x16x32_bf16 v[72:75], v[154:157], v[198:201], v[72:75]
	v_mfma_f32_16x16x32_bf16 v[64:67], v[162:165], v[198:201], v[64:67]
	v_mfma_f32_16x16x32_bf16 v[108:111], v[158:161], v[174:177], v[108:111]
	v_mfma_f32_16x16x32_bf16 v[112:115], v[166:169], v[174:177], v[112:115]
	v_mfma_f32_16x16x32_bf16 v[104:107], v[158:161], v[182:185], v[104:107]
	v_mfma_f32_16x16x32_bf16 v[96:99], v[166:169], v[182:185], v[96:99]
	v_mfma_f32_16x16x32_bf16 v[88:91], v[158:161], v[194:197], v[88:91]
	v_mfma_f32_16x16x32_bf16 v[80:83], v[166:169], v[194:197], v[80:83]
	v_mfma_f32_16x16x32_bf16 v[72:75], v[158:161], v[202:205], v[72:75]
	v_mfma_f32_16x16x32_bf16 v[64:67], v[166:169], v[202:205], v[64:67]
	s_setprio 0
	s_barrier
	s_add_i32 s24, 0, 0x1c000
	s_add_i32 s25, s26, s33
	v_add_u32_e32 v186, s24, v149
	s_add_u32 vcc_lo, s92, s18
	s_addc_u32 vcc_hi, s93, s19
	s_mov_b32 m0, s25
	ds_read_b128 v[206:209], v186
	ds_read_b128 v[210:213], v186 offset:1024
	ds_read_b128 v[214:217], v186 offset:2048
	ds_read_b128 v[218:221], v186 offset:3072
	global_load_lds_dwordx4 v132, vcc
	s_add_i32 m0, s25, 0x2000
	s_nop 0
	global_load_lds_dwordx4 v128, vcc
	s_barrier
; #define PG8_STAGE(bufoff, gbase, voff) do { _Pragma("unroll") for (int _i = 0; _i < 2; ++_i) \
;     __builtin_amdgcn_global_load_lds((const unsigned*)((const char*)(gbase) + (voff)[_i]), (LAS unsigned*)(lds + (bufoff) + ldsw + _i * 8192), 16, 0, 0); } while (0)
; #define PG8_LDA(dst, b, h) do { _Pragma("unroll") for (int m = 0; m < 4; ++m) _Pragma("unroll") for (int k = 0; k < 2; ++k) dst[m][k] = *(const LAS bf16x8*)(lds + PG8_SA(b, h) + aoff + m * 2048 + k * 1024); } while (0)
; #define PG8_LDB(dst, b, h) do { _Pragma("unroll") for (int n = 0; n < 2; ++n) _Pragma("unroll") for (int k = 0; k < 2; ++k) dst[n][k] = *(const LAS bf16x8*)(lds + PG8_SB(b, h) + boff + n * 2048 + k * 1024); } while (0)
; #define PG8_WAIT_V(n) asm volatile("s_waitcnt vmcnt(" #n ")" ::: "memory")
; template <class Epi>
; __device__ __forceinline__ void gemm_phase(LAS unsigned char* lds, const Gemm g, const StaticOrder& S, const Epi& E) {
;     ...
;     for (int t = 0; t < nt; t += 2) {
;       const bool last = (t == nt - 2);
;       const char* a1 = cA + (size_t)(t + 1) * kstep;
;       const char* a2 = last ? nA : cA + (size_t)(t + 2) * kstep; const char* b2 = last ? nB : cB + (size_t)(t + 2) * kstep;
;       const char* a3 = a2 + kstep; const char* b3 = b2 + kstep;
;       PG8_LDB(B0, 0, 0); PG8_SCHED; PG8_LDA(At, 0, 0); PG8_STAGE(PG8_SA(1, 1), a1 + hstep, voffA);
;       PG8_WAIT_L(8); PG8_BAR; PG8_WAIT_L(0); PG8_MMA(0, 0, At, B0); PG8_BAR; PG8_SCHED;
;       PG8_LDB(B1, 0, 1); PG8_STAGE(PG8_SB(0, 0), b2, voffB);
;       PG8_BAR; PG8_WAIT_L(0); PG8_MMA(0, 1, At, B1); PG8_BAR;
;       PG8_LDA(At, 0, 1); PG8_STAGE(PG8_SA(0, 0), a2, voffA);
;       PG8_BAR; PG8_WAIT_L(0); PG8_MMA(1, 0, At, B0); PG8_BAR; PG8_SCHED;
;       PG8_STAGE(PG8_SB(0, 1), b2 + hstep, voffB);
;       PG8_WAIT_V(6); PG8_BAR; PG8_MMA(1, 1, At, B1); PG8_BAR;
;       PG8_LDB(B0, 1, 0); PG8_SCHED; PG8_LDA(At, 1, 0); PG8_STAGE(PG8_SA(0, 1), a2 + hstep, voffA);
;       PG8_WAIT_L(8); PG8_BAR; PG8_WAIT_L(0); PG8_MMA(0, 0, At, B0); PG8_BAR; PG8_SCHED;
;       PG8_LDB(B1, 1, 1); PG8_STAGE(PG8_SB(1, 0), b3, voffB);
;       PG8_BAR; PG8_WAIT_L(0); PG8_MMA(0, 1, At, B1); PG8_BAR;
;       PG8_LDA(At, 1, 1); PG8_STAGE(PG8_SA(1, 0), a3, voffA);
;       PG8_BAR; PG8_WAIT_L(0); PG8_MMA(1, 0, At, B0); PG8_BAR; PG8_SCHED;
;       PG8_STAGE(PG8_SB(1, 1), b3 + hstep, voffB);
;       PG8_WAIT_V(6); PG8_BAR; PG8_MMA(1, 1, At, B1); PG8_BAR;
	s_waitcnt lgkmcnt(0)
	s_setprio 1
	s_waitcnt lgkmcnt(0)
	v_mfma_f32_16x16x32_bf16 v[124:127], v[206:209], v[170:173], v[124:127]
	v_mfma_f32_16x16x32_bf16 v[120:123], v[214:217], v[170:173], v[120:123]
	v_mfma_f32_16x16x32_bf16 v[116:119], v[206:209], v[178:181], v[116:119]
	v_mfma_f32_16x16x32_bf16 v[100:103], v[214:217], v[178:181], v[100:103]
	v_mfma_f32_16x16x32_bf16 v[92:95], v[206:209], v[188:191], v[92:95]
	v_mfma_f32_16x16x32_bf16 v[84:87], v[214:217], v[188:191], v[84:87]
	v_mfma_f32_16x16x32_bf16 v[76:79], v[206:209], v[198:201], v[76:79]
	v_mfma_f32_16x16x32_bf16 v[68:71], v[214:217], v[198:201], v[68:71]
	v_mfma_f32_16x16x32_bf16 v[124:127], v[210:213], v[174:177], v[124:127]
	v_mfma_f32_16x16x32_bf16 v[120:123], v[218:221], v[174:177], v[120:123]
	v_mfma_f32_16x16x32_bf16 v[116:119], v[210:213], v[182:185], v[116:119]
	v_mfma_f32_16x16x32_bf16 v[100:103], v[218:221], v[182:185], v[100:103]
	v_mfma_f32_16x16x32_bf16 v[92:95], v[210:213], v[194:197], v[92:95]
	v_mfma_f32_16x16x32_bf16 v[84:87], v[218:221], v[194:197], v[84:87]
	v_mfma_f32_16x16x32_bf16 v[76:79], v[210:213], v[202:205], v[76:79]
	v_mfma_f32_16x16x32_bf16 v[68:71], v[218:221], v[202:205], v[68:71]
	s_setprio 0
	s_mov_b32 m0, s43
	s_add_u32 vcc_lo, s96, s18
	s_addc_u32 vcc_hi, s97, s19
	s_barrier
	ds_read_b128 v[170:173], v151 offset:49152
	ds_read_b128 v[174:177], v151 offset:50176
	ds_read_b128 v[178:181], v151 offset:51200
	ds_read_b128 v[182:185], v151 offset:52224
	ds_read_b128 v[188:191], v151 offset:53248
	ds_read_b128 v[194:197], v151 offset:54272
	ds_read_b128 v[198:201], v151 offset:55296
	ds_read_b128 v[202:205], v151 offset:56320
	global_load_lds_dwordx4 v134, vcc
	s_mov_b32 m0, s44
	s_nop 0
	global_load_lds_dwordx4 v130, vcc
	s_barrier
	s_waitcnt lgkmcnt(0)
	s_setprio 1
	s_waitcnt lgkmcnt(0)
	v_mfma_f32_16x16x32_bf16 v[56:59], v[154:157], v[170:173], v[56:59]
	v_mfma_f32_16x16x32_bf16 v[52:55], v[162:165], v[170:173], v[52:55]
	v_mfma_f32_16x16x32_bf16 v[40:43], v[154:157], v[178:181], v[40:43]
	v_mfma_f32_16x16x32_bf16 v[36:39], v[162:165], v[178:181], v[36:39]
	v_mfma_f32_16x16x32_bf16 v[24:27], v[154:157], v[188:191], v[24:27]
	v_mfma_f32_16x16x32_bf16 v[20:23], v[162:165], v[188:191], v[20:23]
	v_mfma_f32_16x16x32_bf16 v[8:11], v[154:157], v[198:201], v[8:11]
	v_mfma_f32_16x16x32_bf16 v[4:7], v[162:165], v[198:201], v[4:7]
	v_mfma_f32_16x16x32_bf16 v[56:59], v[158:161], v[174:177], v[56:59]
	v_mfma_f32_16x16x32_bf16 v[52:55], v[166:169], v[174:177], v[52:55]
	v_mfma_f32_16x16x32_bf16 v[40:43], v[158:161], v[182:185], v[40:43]
	v_mfma_f32_16x16x32_bf16 v[36:39], v[166:169], v[182:185], v[36:39]
	v_mfma_f32_16x16x32_bf16 v[24:27], v[158:161], v[194:197], v[24:27]
	v_mfma_f32_16x16x32_bf16 v[20:23], v[166:169], v[194:197], v[20:23]
	v_mfma_f32_16x16x32_bf16 v[8:11], v[158:161], v[202:205], v[8:11]
	v_mfma_f32_16x16x32_bf16 v[4:7], v[166:169], v[202:205], v[4:7]
	s_setprio 0
	s_barrier
	s_add_i32 s24, s24, s33
	s_add_u32 vcc_lo, s100, s18
	s_addc_u32 vcc_hi, s101, s19
	s_mov_b32 m0, s24
	s_nop 0
	global_load_lds_dwordx4 v132, vcc
	s_add_i32 m0, s24, 0x2000
	s_nop 0
	global_load_lds_dwordx4 v128, vcc
	s_waitcnt vmcnt(6)
	s_barrier
	s_setprio 1
	v_mfma_f32_16x16x32_bf16 v[60:63], v[206:209], v[170:173], v[60:63]
	v_mfma_f32_16x16x32_bf16 v[48:51], v[214:217], v[170:173], v[48:51]
	v_mfma_f32_16x16x32_bf16 v[44:47], v[206:209], v[178:181], v[44:47]
	v_mfma_f32_16x16x32_bf16 v[32:35], v[214:217], v[178:181], v[32:35]
	v_mfma_f32_16x16x32_bf16 v[28:31], v[206:209], v[188:191], v[28:31]
	v_mfma_f32_16x16x32_bf16 v[16:19], v[214:217], v[188:191], v[16:19]
	v_mfma_f32_16x16x32_bf16 v[12:15], v[206:209], v[198:201], v[12:15]
	v_mfma_f32_16x16x32_bf16 v[0:3], v[214:217], v[198:201], v[0:3]
	v_mfma_f32_16x16x32_bf16 v[60:63], v[210:213], v[174:177], v[60:63]
	v_mfma_f32_16x16x32_bf16 v[48:51], v[218:221], v[174:177], v[48:51]
	v_mfma_f32_16x16x32_bf16 v[44:47], v[210:213], v[182:185], v[44:47]
	v_mfma_f32_16x16x32_bf16 v[32:35], v[218:221], v[182:185], v[32:35]
	v_mfma_f32_16x16x32_bf16 v[28:31], v[210:213], v[194:197], v[28:31]
	v_mfma_f32_16x16x32_bf16 v[16:19], v[218:221], v[194:197], v[16:19]
	v_mfma_f32_16x16x32_bf16 v[12:15], v[210:213], v[202:205], v[12:15]
	v_mfma_f32_16x16x32_bf16 v[0:3], v[218:221], v[202:205], v[0:3]
	s_setprio 0
	s_add_u32 s0, s0, 0x100
	s_addc_u32 s1, s1, 0
	s_add_u32 s57, s57, 0x100
	s_addc_u32 s58, s58, 0
	s_cmp_ge_i32 s59, s47
	s_mov_b32 s24, s59
	s_barrier
	s_cbranch_scc0 .LBB0_874
	s_branch .LBB0_865
